# rwkv_out: gate-weight fragment loads issued before the mid-unit barrier
# speedup vs baseline: 1.0069x; 1.0024x over previous
; __device__ __forceinline__ void rwkv_out_phase(const bf16* Z, const RwkvW w, const bf16* Wl, const float* Ub, const bf16* RHO, const bf16* Y0, const float* BON, bf16* MIX, unsigned char* lds) {
;     ...
;         f32x4 ya[4], ga[4];
; #pragma unroll
;         for (int dt = 0; dt < 4; ++dt) { ya[dt] = (f32x4){0.f, 0.f, 0.f, 0.f}; ga[dt] = (f32x4){0.f, 0.f, 0.f, 0.f};
; #pragma unroll
;             for (int k0 = 0; k0 < 64; k0 += 32) ya[dt] = mma16(Rs, 72, 16 * wave, Ss, 72, 16 * dt, k0, ya[dt], lane);
;             const bf16* wg = Wl + (size_t)(1024 + col0 + 16 * dt + r16) * 256 + 128 + q4 * 8;
; #pragma unroll
;             for (int ks = 0; ks < 4; ++ks) ga[dt] = __builtin_amdgcn_mfma_f32_16x16x32_bf16(*(const bf16x8*)(AG + (16 * wave + r16) * 136 + 32 * ks + q4 * 8), *(const bf16x8*)(wg + 32 * ks), ga[dt], 0, 0, 0); }
.LBB0_641:
	s_or_b64 exec, exec, s[18:19]
	s_waitcnt lgkmcnt(0)
	v_or_b32_e32 v158, s37, v73
	v_lshlrev_b32_e32 v158, 9, v158
	v_mov_b32_e32 v159, 0
	v_lshl_add_u64 v[158:159], s[12:13], 0, v[158:159]
	v_mov_b32_e32 v160, v66
	v_mov_b32_e32 v161, 0
	v_lshl_add_u64 v[158:159], v[158:159], 0, v[160:161]
	s_mov_b64 s[20:21], 0x80000
	v_lshl_add_u64 v[156:157], v[158:159], 0, s[20:21]
	s_mov_b64 s[20:21], 0x2000
	global_load_dwordx4 v[174:177], v[156:157], off offset:256
	global_load_dwordx4 v[178:181], v[156:157], off offset:320
	global_load_dwordx4 v[182:185], v[156:157], off offset:384
	global_load_dwordx4 v[186:189], v[156:157], off offset:448
	v_lshl_add_u64 v[156:157], v[156:157], 0, s[20:21]
	global_load_dwordx4 v[190:193], v[156:157], off offset:256
	global_load_dwordx4 v[194:197], v[156:157], off offset:320
	global_load_dwordx4 v[198:201], v[156:157], off offset:384
	global_load_dwordx4 v[202:205], v[156:157], off offset:448
	v_lshl_add_u64 v[156:157], v[156:157], 0, s[20:21]
	global_load_dwordx4 v[206:209], v[156:157], off offset:256
	global_load_dwordx4 v[210:213], v[156:157], off offset:320
	global_load_dwordx4 v[214:217], v[156:157], off offset:384
	global_load_dwordx4 v[218:221], v[156:157], off offset:448
	v_lshl_add_u64 v[156:157], v[156:157], 0, s[20:21]
	global_load_dwordx4 v[222:225], v[156:157], off offset:256
	global_load_dwordx4 v[226:229], v[156:157], off offset:320
	global_load_dwordx4 v[230:233], v[156:157], off offset:384
	global_load_dwordx4 v[114:117], v[156:157], off offset:448
	s_barrier
	ds_read_b128 v[30:33], v52
	ds_read_b128 v[2:5], v102 offset:18432
	v_or_b32_e32 v69, s37, v73
	s_waitcnt lgkmcnt(0)
	v_mfma_f32_16x16x32_bf16 v[6:9], v[30:33], v[2:5], 0
	ds_read_b128 v[2:5], v52 offset:64
	ds_read_b128 v[10:13], v102 offset:18496
	v_lshlrev_b32_e32 v0, 9, v69
	v_mov_b32_e32 v67, v1
	s_waitcnt lgkmcnt(0)
	v_mfma_f32_16x16x32_bf16 v[18:21], v[2:5], v[10:13], v[6:9]
	s_mov_b64 s[18:19], 0x80100
	s_nop 1
	v_lshl_add_u64 v[6:7], s[12:13], 0, v[0:1]
	v_lshl_add_u64 v[70:71], v[6:7], 0, v[66:67]
	v_lshl_add_u64 v[14:15], v[70:71], 0, s[18:19]
	s_mov_b32 s18, 0x80000
	v_add_co_u32_e32 v6, vcc, s18, v70
	s_nop 0
	v_addc_co_u32_e32 v7, vcc, 0, v71, vcc
	ds_read_b128 v[38:41], v53 offset:27648
	ds_read_b128 v[34:37], v53 offset:27712
	ds_read_b128 v[42:45], v53 offset:27776
	ds_read_b128 v[46:49], v53 offset:27840
	s_mov_b64 s[18:19], 0x82100
	v_lshl_add_u64 v[26:27], v[70:71], 0, s[18:19]
	s_mov_b32 s18, 0x82000
	s_mov_b32 s20, 0x800000
	s_movk_i32 s21, 0x1000
	s_mov_b32 s25, s61
	s_waitcnt lgkmcnt(3)
	s_waitcnt vmcnt(15)
	v_mfma_f32_16x16x32_bf16 v[6:9], v[38:41], v[174:177], 0
	s_waitcnt lgkmcnt(2)
	s_waitcnt vmcnt(14)
	v_mfma_f32_16x16x32_bf16 v[6:9], v[34:37], v[178:181], v[6:9]
	s_waitcnt lgkmcnt(1)
	s_waitcnt vmcnt(13)
	v_mfma_f32_16x16x32_bf16 v[6:9], v[42:45], v[182:185], v[6:9]
	ds_read_b128 v[14:17], v102 offset:20800
	s_waitcnt lgkmcnt(1)
	s_waitcnt vmcnt(12)
	v_mfma_f32_16x16x32_bf16 v[6:9], v[46:49], v[186:189], v[6:9]
	ds_read_b128 v[10:13], v102 offset:20736
	s_waitcnt lgkmcnt(0)
	v_mfma_f32_16x16x32_bf16 v[10:13], v[30:33], v[10:13], 0
	v_mfma_f32_16x16x32_bf16 v[22:25], v[2:5], v[14:17], v[10:13]
	s_nop 5
	v_add_co_u32_e32 v10, vcc, s18, v70
	s_mov_b64 s[18:19], 0x84100
	s_nop 0
	v_addc_co_u32_e32 v11, vcc, 0, v71, vcc
	v_lshl_add_u64 v[112:113], v[70:71], 0, s[18:19]
	s_mov_b32 s18, 0x84000
	s_waitcnt vmcnt(11)
	v_mfma_f32_16x16x32_bf16 v[10:13], v[38:41], v[190:193], 0
	s_waitcnt vmcnt(10)
	v_mfma_f32_16x16x32_bf16 v[10:13], v[34:37], v[194:197], v[10:13]
	s_waitcnt vmcnt(9)
	v_mfma_f32_16x16x32_bf16 v[10:13], v[42:45], v[198:201], v[10:13]
	ds_read_b128 v[26:29], v102 offset:23104
	s_waitcnt vmcnt(8)
	v_mfma_f32_16x16x32_bf16 v[10:13], v[46:49], v[202:205], v[10:13]
	ds_read_b128 v[14:17], v102 offset:23040
	s_waitcnt lgkmcnt(0)
	v_mfma_f32_16x16x32_bf16 v[14:17], v[30:33], v[14:17], 0
	v_mfma_f32_16x16x32_bf16 v[26:29], v[2:5], v[26:29], v[14:17]
	s_nop 6
	v_add_co_u32_e32 v14, vcc, s18, v70
	s_mov_b64 s[18:19], 0x86100
	s_nop 0
	v_addc_co_u32_e32 v15, vcc, 0, v71, vcc
	s_waitcnt vmcnt(7)
	v_mfma_f32_16x16x32_bf16 v[14:17], v[38:41], v[206:209], 0
	s_waitcnt vmcnt(6)
	v_mfma_f32_16x16x32_bf16 v[14:17], v[34:37], v[210:213], v[14:17]
	s_waitcnt vmcnt(5)
	v_mfma_f32_16x16x32_bf16 v[14:17], v[42:45], v[214:217], v[14:17]
	s_waitcnt vmcnt(4)
	v_mfma_f32_16x16x32_bf16 v[14:17], v[46:49], v[218:221], v[14:17]
	ds_read_b128 v[108:111], v102 offset:25344
	s_waitcnt lgkmcnt(0)
	v_mfma_f32_16x16x32_bf16 v[30:33], v[30:33], v[108:111], 0
	ds_read_b128 v[108:111], v102 offset:25408
	s_waitcnt lgkmcnt(0)
	v_mfma_f32_16x16x32_bf16 v[30:33], v[2:5], v[108:111], v[30:33]
	v_lshl_add_u64 v[108:109], v[70:71], 0, s[18:19]
	s_mov_b32 s18, 0x86000
	v_add_co_u32_e32 v2, vcc, s18, v70
	s_lshl_b32 s18, s38, 2
	s_nop 0
	v_addc_co_u32_e32 v3, vcc, 0, v71, vcc
	s_add_u32 s18, s35, s18
	s_addc_u32 s19, s36, 0
	s_lshl_b32 s60, s37, 1
	s_add_i32 s26, s26, s70
	s_cmpk_gt_i32 s26, 0x7ff
	s_waitcnt vmcnt(3)
	v_mfma_f32_16x16x32_bf16 v[2:5], v[38:41], v[222:225], 0
	s_waitcnt vmcnt(2)
	v_mfma_f32_16x16x32_bf16 v[2:5], v[34:37], v[226:229], v[2:5]
	v_mov_b32_e32 v38, v18
	v_mov_b32_e32 v39, v22
	s_waitcnt vmcnt(1)
	v_mfma_f32_16x16x32_bf16 v[2:5], v[42:45], v[230:233], v[2:5]
	s_waitcnt vmcnt(0)
; __device__ __forceinline__ float bf2f(bf16 v) { return __uint_as_float(((unsigned)v) << 16); }
; __device__ __forceinline__ unsigned f2bf(float f) { return pk2(f, f) & 0xffffu; }
; __device__ __forceinline__ float red16(float v) { v += dpp_mov<0xB1>(v); v += dpp_mov<0x4E>(v); v += dpp_mov<0x141>(v); v += dpp_mov<0x140>(v); return v; }
; __device__ __forceinline__ void rwkv_out_phase(const bf16* Z, const RwkvW w, const bf16* Wl, const float* Ub, const bf16* RHO, const bf16* Y0, const float* BON, bf16* MIX, unsigned char* lds) {
;     ...
;         for (int jj = 0; jj < 4; ++jj) { const int tl = 16 * wave + q4 * 4 + jj; const float bon = BON[(rowbase + tl) * 8 + h];
;             float y[4]; float sum = 0.f;
; #pragma unroll
;             for (int dt = 0; dt < 4; ++dt) { y[dt] = ya[dt][jj] + bf2f(Ys[tl * 72 + 16 * dt + r16]); sum += y[dt]; }
;             const float mean = red16(sum) * (1.f / 64.f); float qq = 0.f;
; #pragma unroll
;             for (int dt = 0; dt < 4; ++dt) { y[dt] -= mean; qq += y[dt] * y[dt]; }
;             const float rstd = rsqrtf(red16(qq) * (1.f / 64.f) + 64e-5f);
; #pragma unroll
;             for (int dt = 0; dt < 4; ++dt) { const int ch = 16 * dt + r16; const float vc = bf2f(Vs[(tl + 1) * 72 + ch]), vp = bf2f(Vs[tl * 72 + ch]);
;                 const float vs = vc + w.mu[1024 + col0 + ch] * (vp - vc);
;                 Ys[tl * 72 + ch] = (bf16)f2bf((y[dt] * rstd * w.ln_g[col0 + ch] + w.ln_b[col0 + ch] + bon * vs) * ga[dt][jj]); } }
	v_mfma_f32_16x16x32_bf16 v[2:5], v[46:49], v[114:117], v[2:5]
	v_lshl_add_u64 v[34:35], s[16:17], 0, v[54:55]
	v_lshlrev_b64 v[34:35], 5, v[34:35]
	v_lshl_add_u64 v[34:35], s[18:19], 0, v[34:35]
	global_load_dword v43, v[34:35], off
	v_add_lshl_u32 v118, s37, v73, 2
	v_mov_b32_e32 v119, 0
	global_load_dword v120, v118, s[8:9]
	global_load_dword v121, v118, s[10:11]
	global_load_dword v122, v118, s[8:9] offset:64
	global_load_dword v123, v118, s[10:11] offset:64
	global_load_dword v138, v118, s[8:9] offset:128
	global_load_dword v139, v118, s[10:11] offset:128
	global_load_dword v140, v118, s[8:9] offset:192
	global_load_dword v141, v118, s[10:11] offset:192
	v_lshl_add_u64 v[124:125], s[6:7], 0, v[118:119]
	v_add_co_u32_e32 v124, vcc, 0x1000, v124
	s_nop 1
	v_addc_co_u32_e32 v125, vcc, 0, v125, vcc
	global_load_dword v126, v[124:125], off
	global_load_dword v127, v[124:125], off offset:64
	global_load_dword v128, v[124:125], off offset:128
	global_load_dword v129, v[124:125], off offset:192
	v_lshl_add_u64 v[136:137], s[16:17], 0, v[58:59]
	v_lshlrev_b64 v[136:137], 5, v[136:137]
	v_lshl_add_u64 v[136:137], s[18:19], 0, v[136:137]
	global_load_dword v132, v[136:137], off
	v_lshl_add_u64 v[136:137], s[16:17], 0, v[60:61]
	v_lshlrev_b64 v[136:137], 5, v[136:137]
	v_lshl_add_u64 v[136:137], s[18:19], 0, v[136:137]
	global_load_dword v133, v[136:137], off
	v_lshl_add_u64 v[136:137], s[16:17], 0, v[62:63]
	v_lshlrev_b64 v[136:137], 5, v[136:137]
	v_lshl_add_u64 v[136:137], s[18:19], 0, v[136:137]
	global_load_dword v134, v[136:137], off
	ds_read_u16 v0, v103 offset:62560
	ds_read_u16 v34, v103 offset:62528
	v_mov_b32_e32 v37, v26
	v_mov_b32_e32 v36, v30
	s_waitcnt lgkmcnt(0)
	v_lshlrev_b32_e32 v35, 16, v34
	v_lshlrev_b32_e32 v34, 16, v0
	ds_read_u16 v0, v103 offset:62464
	ds_read_u16 v26, v103 offset:62496
	v_pk_add_f32 v[34:35], v[36:37], v[34:35]
	s_waitcnt lgkmcnt(1)
	v_lshlrev_b32_e32 v36, 16, v0
	s_waitcnt lgkmcnt(0)
	v_lshlrev_b32_e32 v37, 16, v26
	v_pk_add_f32 v[36:37], v[38:39], v[36:37]
	s_nop 0
	v_add_f32_e32 v0, 0, v36
	v_add_f32_e32 v0, v0, v37
	v_add_f32_e32 v0, v0, v35
	v_add_f32_e32 v0, v0, v34
	s_nop 1
	v_add_f32_dpp v0, v0, v0 quad_perm:[1,0,3,2] row_mask:0xf bank_mask:0xf bound_ctrl:1
	s_nop 1
	v_add_f32_dpp v0, v0, v0 quad_perm:[2,3,0,1] row_mask:0xf bank_mask:0xf bound_ctrl:1
	s_nop 1
	v_add_f32_dpp v0, v0, v0 row_half_mirror row_mask:0xf bank_mask:0xf bound_ctrl:1
	s_nop 1
	v_add_f32_dpp v0, v0, v0 row_mirror row_mask:0xf bank_mask:0xf bound_ctrl:1
	v_mul_f32_e32 v0, 0x3c800000, v0
	v_pk_add_f32 v[36:37], v[36:37], v[0:1] op_sel_hi:[1,0] neg_lo:[0,1] neg_hi:[0,1]
	v_pk_add_f32 v[34:35], v[34:35], v[0:1] op_sel_hi:[1,0] neg_lo:[0,1] neg_hi:[0,1]
	v_pk_mul_f32 v[38:39], v[36:37], v[36:37]
	v_pk_mul_f32 v[40:41], v[34:35], v[34:35]
	v_add_f32_e32 v0, v38, v39
	v_add_f32_e32 v0, v41, v0
	v_add_f32_e32 v0, v40, v0
	s_nop 1
	v_add_f32_dpp v0, v0, v0 quad_perm:[1,0,3,2] row_mask:0xf bank_mask:0xf bound_ctrl:1
	s_nop 1
	v_add_f32_dpp v0, v0, v0 quad_perm:[2,3,0,1] row_mask:0xf bank_mask:0xf bound_ctrl:1
	s_nop 1
	v_add_f32_dpp v0, v0, v0 row_half_mirror row_mask:0xf bank_mask:0xf bound_ctrl:1
	s_nop 1
	v_add_f32_dpp v0, v0, v0 row_mirror row_mask:0xf bank_mask:0xf bound_ctrl:1
	v_fmamk_f32 v0, v0, 0x3c800000, v167
	v_cmp_gt_f32_e32 vcc, s20, v0
	v_mul_f32_e32 v18, 0x4b800000, v0
	s_nop 0
	v_cndmask_b32_e32 v0, v0, v18, vcc
	v_rsq_f32_e32 v0, v0
	s_nop 0
	v_mul_f32_e32 v18, 0x45800000, v0
	v_cndmask_b32_e32 v18, v0, v18, vcc
	ds_read_u16 v0, v74 offset:144
	s_waitcnt lgkmcnt(0)
	v_lshlrev_b32_e32 v22, 16, v0
	ds_read_u16 v0, v75
	s_waitcnt lgkmcnt(0)
	v_lshlrev_b32_e32 v26, 16, v0
	v_lshlrev_b32_e32 v0, 2, v69
	v_lshl_add_u64 v[38:39], s[6:7], 0, v[0:1]
	v_add_co_u32_e32 v38, vcc, s21, v38
	v_sub_f32_e32 v26, v26, v22
	s_nop 0
	v_addc_co_u32_e32 v39, vcc, 0, v39, vcc
	s_waitcnt vmcnt(0)
	v_mov_b32_e32 v30, v126
	v_mov_b32_e32 v69, v1
	s_waitcnt vmcnt(0)
	v_fmac_f32_e32 v22, v30, v26
	v_mul_f32_e32 v26, v36, v18
	v_mov_b32_e32 v36, v120
	v_mov_b32_e32 v38, v121
	s_waitcnt vmcnt(0)
	v_fma_f32 v0, v36, v26, v38
	v_fmac_f32_e32 v0, v43, v22
	v_mul_f32_e32 v0, v6, v0
	v_cvt_pk_bf16_f32 v0, v0, v0
	ds_write_b16 v76, v0 offset:62464
	ds_read_u16 v0, v74 offset:176
	ds_read_u16 v6, v74 offset:208
	s_waitcnt lgkmcnt(1)
	v_lshlrev_b32_e32 v22, 16, v0
	ds_read_u16 v0, v77
	s_waitcnt lgkmcnt(1)
	v_lshlrev_b32_e32 v6, 16, v6
	s_waitcnt lgkmcnt(0)
	v_lshlrev_b32_e32 v26, 16, v0
	v_add_lshl_u32 v0, s37, v73, 2
	v_lshl_add_u64 v[40:41], s[6:7], 0, v[0:1]
	v_add_co_u32_e32 v44, vcc, s21, v40
	v_sub_f32_e32 v26, v26, v22
	s_nop 0
	v_addc_co_u32_e32 v45, vcc, 0, v41, vcc
	v_mov_b32_e32 v39, v127
	s_waitcnt vmcnt(0)
	v_fmac_f32_e32 v22, v39, v26
	v_mul_f32_e32 v26, v37, v18
	v_mov_b32_e32 v37, v122
	v_mov_b32_e32 v40, v123
	v_mov_b32_e32 v41, v128
	s_waitcnt vmcnt(1)
	v_fma_f32 v26, v37, v26, v40
	v_fmac_f32_e32 v26, v43, v22
	v_mul_f32_e32 v10, v10, v26
	v_cvt_pk_bf16_f32 v10, v10, v10
	ds_write_b16 v78, v10 offset:62496
	ds_read_u16 v10, v79
	v_mov_b32_e32 v26, v31
	v_mov_b32_e32 v22, v19
	s_waitcnt lgkmcnt(0)
	v_lshlrev_b32_e32 v10, 16, v10
	v_sub_f32_e32 v10, v10, v6
	s_waitcnt vmcnt(0)
	v_fmac_f32_e32 v6, v41, v10
	v_mul_f32_e32 v10, v35, v18
	v_mov_b32_e32 v42, v138
	v_mov_b32_e32 v35, v139
	v_mul_f32_e32 v18, v34, v18
	s_waitcnt vmcnt(0)
	v_fma_f32 v10, v42, v10, v35
	v_fmac_f32_e32 v10, v43, v6
	v_mul_f32_e32 v6, v14, v10
	v_cvt_pk_bf16_f32 v6, v6, v6
	ds_write_b16 v78, v6 offset:62528
	ds_read_u16 v6, v74 offset:240
	ds_read_u16 v10, v80
	s_waitcnt lgkmcnt(1)
	v_lshlrev_b32_e32 v6, 16, v6
	s_waitcnt lgkmcnt(0)
; __device__ __forceinline__ float bf2f(bf16 v) { return __uint_as_float(((unsigned)v) << 16); }
; __device__ __forceinline__ unsigned f2bf(float f) { return pk2(f, f) & 0xffffu; }
; __device__ __forceinline__ float red16(float v) { v += dpp_mov<0xB1>(v); v += dpp_mov<0x4E>(v); v += dpp_mov<0x141>(v); v += dpp_mov<0x140>(v); return v; }
; __device__ __forceinline__ void rwkv_out_phase(const bf16* Z, const RwkvW w, const bf16* Wl, const float* Ub, const bf16* RHO, const bf16* Y0, const float* BON, bf16* MIX, unsigned char* lds) {
;     ...
;         for (int jj = 0; jj < 4; ++jj) { const int tl = 16 * wave + q4 * 4 + jj; const float bon = BON[(rowbase + tl) * 8 + h];
;             float y[4]; float sum = 0.f;
; #pragma unroll
;             for (int dt = 0; dt < 4; ++dt) { y[dt] = ya[dt][jj] + bf2f(Ys[tl * 72 + 16 * dt + r16]); sum += y[dt]; }
;             const float mean = red16(sum) * (1.f / 64.f); float qq = 0.f;
; #pragma unroll
;             for (int dt = 0; dt < 4; ++dt) { y[dt] -= mean; qq += y[dt] * y[dt]; }
;             const float rstd = rsqrtf(red16(qq) * (1.f / 64.f) + 64e-5f);
; #pragma unroll
;             for (int dt = 0; dt < 4; ++dt) { const int ch = 16 * dt + r16; const float vc = bf2f(Vs[(tl + 1) * 72 + ch]), vp = bf2f(Vs[tl * 72 + ch]);
;                 const float vs = vc + w.mu[1024 + col0 + ch] * (vp - vc);
;                 Ys[tl * 72 + ch] = (bf16)f2bf((y[dt] * rstd * w.ln_g[col0 + ch] + w.ln_b[col0 + ch] + bon * vs) * ga[dt][jj]); } }
	v_lshlrev_b32_e32 v14, 16, v10
	v_mov_b32_e32 v10, v129
	v_sub_f32_e32 v14, v14, v6
	v_lshl_add_u64 v[44:45], s[16:17], 0, v[58:59]
	v_lshlrev_b64 v[44:45], 5, v[44:45]
	v_lshl_add_u64 v[44:45], s[18:19], 0, v[44:45]
	s_waitcnt vmcnt(0)
	v_fmac_f32_e32 v6, v10, v14
	v_mov_b32_e32 v14, v140
	s_nop 0
	v_mov_b32_e32 v0, v141
	s_waitcnt vmcnt(0)
	v_fma_f32 v18, v18, v14, v0
	v_fmac_f32_e32 v18, v43, v6
	v_mul_f32_e32 v2, v2, v18
	v_cvt_pk_bf16_f32 v2, v2, v2
	ds_write_b16 v78, v2 offset:62560
	v_mov_b32_e32 v2, v132
	ds_read_u16 v6, v103 offset:62704
	ds_read_u16 v18, v103 offset:62672
	s_waitcnt lgkmcnt(1)
	v_lshlrev_b32_e32 v44, 16, v6
	s_waitcnt lgkmcnt(0)
	v_lshlrev_b32_e32 v45, 16, v18
	ds_read_u16 v6, v103 offset:62608
	ds_read_u16 v18, v103 offset:62640
	v_pk_add_f32 v[26:27], v[26:27], v[44:45]
	s_waitcnt lgkmcnt(1)
	v_lshlrev_b32_e32 v44, 16, v6
	s_waitcnt lgkmcnt(0)
	v_lshlrev_b32_e32 v45, 16, v18
	v_pk_add_f32 v[18:19], v[22:23], v[44:45]
	s_nop 0
	v_add_f32_e32 v6, 0, v18
	v_add_f32_e32 v6, v6, v19
	v_add_f32_e32 v6, v6, v27
	v_add_f32_e32 v6, v6, v26
	s_nop 1
	v_add_f32_dpp v6, v6, v6 quad_perm:[1,0,3,2] row_mask:0xf bank_mask:0xf bound_ctrl:1
	s_nop 1
	v_add_f32_dpp v6, v6, v6 quad_perm:[2,3,0,1] row_mask:0xf bank_mask:0xf bound_ctrl:1
	s_nop 1
	v_add_f32_dpp v6, v6, v6 row_half_mirror row_mask:0xf bank_mask:0xf bound_ctrl:1
	s_nop 1
	v_add_f32_dpp v6, v6, v6 row_mirror row_mask:0xf bank_mask:0xf bound_ctrl:1
	v_mul_f32_e32 v6, 0x3c800000, v6
	v_pk_add_f32 v[22:23], v[18:19], v[6:7] op_sel_hi:[1,0] neg_lo:[0,1] neg_hi:[0,1]
	v_pk_add_f32 v[18:19], v[26:27], v[6:7] op_sel_hi:[1,0] neg_lo:[0,1] neg_hi:[0,1]
	v_pk_mul_f32 v[44:45], v[22:23], v[22:23]
	v_pk_mul_f32 v[26:27], v[18:19], v[18:19]
	v_add_f32_e32 v6, v44, v45
	v_add_f32_e32 v6, v27, v6
	v_add_f32_e32 v6, v26, v6
	ds_read_u16 v27, v82
	s_waitcnt lgkmcnt(0)
	v_lshlrev_b32_e32 v27, 16, v27
	v_add_f32_dpp v6, v6, v6 quad_perm:[1,0,3,2] row_mask:0xf bank_mask:0xf bound_ctrl:1
	s_nop 1
	v_add_f32_dpp v6, v6, v6 quad_perm:[2,3,0,1] row_mask:0xf bank_mask:0xf bound_ctrl:1
	s_nop 1
	v_add_f32_dpp v6, v6, v6 row_half_mirror row_mask:0xf bank_mask:0xf bound_ctrl:1
	s_nop 1
	v_add_f32_dpp v6, v6, v6 row_mirror row_mask:0xf bank_mask:0xf bound_ctrl:1
	v_fmamk_f32 v6, v6, 0x3c800000, v167
	v_cmp_gt_f32_e32 vcc, s20, v6
	v_mul_f32_e32 v26, 0x4b800000, v6
	s_nop 0
	v_cndmask_b32_e32 v6, v6, v26, vcc
	v_rsq_f32_e32 v6, v6
	s_nop 0
	v_mul_f32_e32 v26, 0x45800000, v6
	v_cndmask_b32_e32 v6, v6, v26, vcc
	ds_read_u16 v26, v81 offset:144
	v_mul_f32_e32 v22, v22, v6
	v_fma_f32 v22, v36, v22, v38
	s_waitcnt lgkmcnt(0)
	v_lshlrev_b32_e32 v26, 16, v26
	v_sub_f32_e32 v27, v27, v26
	v_fmac_f32_e32 v26, v30, v27
	s_waitcnt vmcnt(0)
	v_fmac_f32_e32 v22, v2, v26
	v_mul_f32_e32 v7, v7, v22
	v_cvt_pk_bf16_f32 v7, v7, v7
	ds_write_b16 v83, v7 offset:62464
	ds_read_u16 v7, v81 offset:176
	ds_read_u16 v22, v84
	s_waitcnt lgkmcnt(1)
	v_lshlrev_b32_e32 v7, 16, v7
	s_waitcnt lgkmcnt(0)
	v_lshlrev_b32_e32 v22, 16, v22
	v_sub_f32_e32 v22, v22, v7
	v_fmac_f32_e32 v7, v39, v22
	v_mul_f32_e32 v22, v23, v6
	v_fma_f32 v22, v37, v22, v40
	v_fmac_f32_e32 v22, v2, v7
	v_mul_f32_e32 v7, v11, v22
	v_cvt_pk_bf16_f32 v7, v7, v7
	ds_write_b16 v83, v7 offset:62496
	ds_read_u16 v7, v81 offset:208
	ds_read_u16 v11, v85
	s_waitcnt lgkmcnt(1)
	v_lshlrev_b32_e32 v7, 16, v7
	s_waitcnt lgkmcnt(0)
	v_lshlrev_b32_e32 v11, 16, v11
	v_sub_f32_e32 v11, v11, v7
	v_fmac_f32_e32 v7, v41, v11
	v_mul_f32_e32 v11, v19, v6
	v_fma_f32 v11, v42, v11, v35
	v_fmac_f32_e32 v11, v2, v7
	v_mul_f32_e32 v7, v15, v11
	v_cvt_pk_bf16_f32 v7, v7, v7
	ds_write_b16 v83, v7 offset:62528
	ds_read_u16 v7, v81 offset:240
	ds_read_u16 v11, v86
	v_mul_f32_e32 v6, v18, v6
	v_fma_f32 v6, v14, v6, v0
	v_mov_b32_e32 v18, v20
	s_waitcnt lgkmcnt(1)
	v_lshlrev_b32_e32 v7, 16, v7
	s_waitcnt lgkmcnt(0)
	v_lshlrev_b32_e32 v11, 16, v11
	v_sub_f32_e32 v11, v11, v7
	v_fmac_f32_e32 v7, v10, v11
	v_fmac_f32_e32 v6, v2, v7
	v_mul_f32_e32 v2, v3, v6
	v_cvt_pk_bf16_f32 v2, v2, v2
	ds_write_b16 v83, v2 offset:62560
	v_lshl_add_u64 v[2:3], s[16:17], 0, v[60:61]
	v_lshlrev_b64 v[2:3], 5, v[2:3]
	v_lshl_add_u64 v[2:3], s[18:19], 0, v[2:3]
	v_mov_b32_e32 v11, v133
	ds_read_u16 v2, v104 offset:62560
	ds_read_u16 v3, v104 offset:62528
	v_mov_b32_e32 v6, v32
	v_mov_b32_e32 v7, v28
	v_mov_b32_e32 v19, v24
	s_waitcnt lgkmcnt(1)
	v_lshlrev_b32_e32 v2, 16, v2
	s_waitcnt lgkmcnt(0)
	v_lshlrev_b32_e32 v3, 16, v3
	v_pk_add_f32 v[2:3], v[6:7], v[2:3]
	ds_read_u16 v6, v104 offset:62464
	ds_read_u16 v7, v104 offset:62496
	v_mov_b32_e32 v24, v21
	v_mov_b32_e32 v28, v33
	s_waitcnt lgkmcnt(1)
	v_lshlrev_b32_e32 v6, 16, v6
	s_waitcnt lgkmcnt(0)
	v_lshlrev_b32_e32 v7, 16, v7
	v_pk_add_f32 v[6:7], v[18:19], v[6:7]
	s_nop 0
	v_add_f32_e32 v15, 0, v6
	v_add_f32_e32 v15, v15, v7
	v_add_f32_e32 v15, v15, v3
	v_add_f32_e32 v15, v15, v2
	s_nop 1
	v_add_f32_dpp v15, v15, v15 quad_perm:[1,0,3,2] row_mask:0xf bank_mask:0xf bound_ctrl:1
	s_nop 1
	v_add_f32_dpp v15, v15, v15 quad_perm:[2,3,0,1] row_mask:0xf bank_mask:0xf bound_ctrl:1
	s_nop 1
	v_add_f32_dpp v15, v15, v15 row_half_mirror row_mask:0xf bank_mask:0xf bound_ctrl:1
	s_nop 1
	v_add_f32_dpp v15, v15, v15 row_mirror row_mask:0xf bank_mask:0xf bound_ctrl:1
	v_mul_f32_e32 v18, 0x3c800000, v15
	v_pk_add_f32 v[6:7], v[6:7], v[18:19] op_sel_hi:[1,0] neg_lo:[0,1] neg_hi:[0,1]
	v_pk_add_f32 v[2:3], v[2:3], v[18:19] op_sel_hi:[1,0] neg_lo:[0,1] neg_hi:[0,1]
	v_pk_mul_f32 v[22:23], v[6:7], v[6:7]
	v_pk_mul_f32 v[18:19], v[2:3], v[2:3]
	v_add_f32_e32 v15, v22, v23
	v_add_f32_e32 v15, v19, v15
	v_add_f32_e32 v15, v18, v15
	ds_read_u16 v19, v88
	s_waitcnt lgkmcnt(0)
; __device__ __forceinline__ float bf2f(bf16 v) { return __uint_as_float(((unsigned)v) << 16); }
; __device__ __forceinline__ unsigned f2bf(float f) { return pk2(f, f) & 0xffffu; }
; __device__ __forceinline__ float red16(float v) { v += dpp_mov<0xB1>(v); v += dpp_mov<0x4E>(v); v += dpp_mov<0x141>(v); v += dpp_mov<0x140>(v); return v; }
; __device__ __forceinline__ void rwkv_out_phase(const bf16* Z, const RwkvW w, const bf16* Wl, const float* Ub, const bf16* RHO, const bf16* Y0, const float* BON, bf16* MIX, unsigned char* lds) {
;     ...
;         for (int jj = 0; jj < 4; ++jj) { const int tl = 16 * wave + q4 * 4 + jj; const float bon = BON[(rowbase + tl) * 8 + h];
;             float y[4]; float sum = 0.f;
; #pragma unroll
;             for (int dt = 0; dt < 4; ++dt) { y[dt] = ya[dt][jj] + bf2f(Ys[tl * 72 + 16 * dt + r16]); sum += y[dt]; }
;             const float mean = red16(sum) * (1.f / 64.f); float qq = 0.f;
; #pragma unroll
;             for (int dt = 0; dt < 4; ++dt) { y[dt] -= mean; qq += y[dt] * y[dt]; }
;             const float rstd = rsqrtf(red16(qq) * (1.f / 64.f) + 64e-5f);
; #pragma unroll
;             for (int dt = 0; dt < 4; ++dt) { const int ch = 16 * dt + r16; const float vc = bf2f(Vs[(tl + 1) * 72 + ch]), vp = bf2f(Vs[tl * 72 + ch]);
;                 const float vs = vc + w.mu[1024 + col0 + ch] * (vp - vc);
;                 Ys[tl * 72 + ch] = (bf16)f2bf((y[dt] * rstd * w.ln_g[col0 + ch] + w.ln_b[col0 + ch] + bon * vs) * ga[dt][jj]); } }
; #pragma unroll
;         for (int t2 = 0; t2 < 2; ++t2) { const int cidx = lane + 64 * t2, i = 16 * wave + (cidx >> 3), c8 = (cidx & 7) * 8;
;             *(u32x4*)(MIX + (rowbase + i) * DM + 512 + col0 + c8) = *(const u32x4*)(Ys + i * 72 + c8); }
	v_lshlrev_b32_e32 v19, 16, v19
	v_add_f32_dpp v15, v15, v15 quad_perm:[1,0,3,2] row_mask:0xf bank_mask:0xf bound_ctrl:1
	s_nop 1
	v_add_f32_dpp v15, v15, v15 quad_perm:[2,3,0,1] row_mask:0xf bank_mask:0xf bound_ctrl:1
	s_nop 1
	v_add_f32_dpp v15, v15, v15 row_half_mirror row_mask:0xf bank_mask:0xf bound_ctrl:1
	s_nop 1
	v_add_f32_dpp v15, v15, v15 row_mirror row_mask:0xf bank_mask:0xf bound_ctrl:1
	v_fmamk_f32 v15, v15, 0x3c800000, v167
	v_cmp_gt_f32_e32 vcc, s20, v15
	v_mul_f32_e32 v18, 0x4b800000, v15
	s_nop 0
	v_cndmask_b32_e32 v15, v15, v18, vcc
	v_rsq_f32_e32 v15, v15
	s_nop 0
	v_mul_f32_e32 v18, 0x45800000, v15
	v_cndmask_b32_e32 v15, v15, v18, vcc
	ds_read_u16 v18, v87 offset:144
	v_mul_f32_e32 v6, v6, v15
	v_fma_f32 v6, v36, v6, v38
	v_mul_f32_e32 v7, v7, v15
	v_fma_f32 v7, v37, v7, v40
	s_waitcnt lgkmcnt(0)
	v_lshlrev_b32_e32 v18, 16, v18
	v_sub_f32_e32 v19, v19, v18
	v_fmac_f32_e32 v18, v30, v19
	v_mul_f32_e32 v3, v3, v15
	v_fma_f32 v3, v42, v3, v35
	v_mul_f32_e32 v2, v2, v15
	v_fma_f32 v2, v14, v2, v0
	s_waitcnt vmcnt(0)
	v_fmac_f32_e32 v6, v11, v18
	v_mul_f32_e32 v6, v8, v6
	v_cvt_pk_bf16_f32 v6, v6, v6
	ds_write_b16 v89, v6 offset:62464
	ds_read_u16 v6, v87 offset:176
	ds_read_u16 v8, v87 offset:208
	ds_read_u16 v18, v90
	s_waitcnt lgkmcnt(2)
	v_lshlrev_b32_e32 v6, 16, v6
	s_waitcnt lgkmcnt(0)
	v_lshlrev_b32_e32 v18, 16, v18
	v_sub_f32_e32 v18, v18, v6
	v_fmac_f32_e32 v6, v39, v18
	v_fmac_f32_e32 v7, v11, v6
	v_mul_f32_e32 v6, v12, v7
	v_cvt_pk_bf16_f32 v6, v6, v6
	ds_write_b16 v91, v6 offset:62496
	ds_read_u16 v7, v92
	v_lshlrev_b32_e32 v6, 16, v8
	s_waitcnt lgkmcnt(0)
	v_lshlrev_b32_e32 v7, 16, v7
	v_sub_f32_e32 v7, v7, v6
	v_fmac_f32_e32 v6, v41, v7
	v_fmac_f32_e32 v3, v11, v6
	v_mul_f32_e32 v3, v16, v3
	v_cvt_pk_bf16_f32 v3, v3, v3
	ds_write_b16 v91, v3 offset:62528
	ds_read_u16 v3, v87 offset:240
	ds_read_u16 v6, v93
	s_waitcnt lgkmcnt(1)
	v_lshlrev_b32_e32 v3, 16, v3
	s_waitcnt lgkmcnt(0)
	v_lshlrev_b32_e32 v6, 16, v6
	v_sub_f32_e32 v6, v6, v3
	v_fmac_f32_e32 v3, v10, v6
	v_fmac_f32_e32 v2, v11, v3
	v_mul_f32_e32 v2, v4, v2
	v_cvt_pk_bf16_f32 v2, v2, v2
	ds_write_b16 v91, v2 offset:62560
	v_lshl_add_u64 v[2:3], s[16:17], 0, v[62:63]
	v_lshlrev_b64 v[2:3], 5, v[2:3]
	v_lshl_add_u64 v[2:3], s[18:19], 0, v[2:3]
	v_mov_b32_e32 v4, v134
	ds_read_u16 v2, v104 offset:62704
	ds_read_u16 v3, v104 offset:62672
	ds_read_u16 v6, v104 offset:62608
	ds_read_u16 v7, v104 offset:62640
	ds_read_u16 v12, v95
	s_waitcnt lgkmcnt(4)
	v_lshlrev_b32_e32 v2, 16, v2
	s_waitcnt lgkmcnt(2)
	v_lshlrev_b32_e32 v6, 16, v6
	s_waitcnt lgkmcnt(1)
	v_lshlrev_b32_e32 v7, 16, v7
	v_pk_add_f32 v[6:7], v[24:25], v[6:7]
	v_lshlrev_b32_e32 v3, 16, v3
	v_add_f32_e32 v8, 0, v6
	v_pk_add_f32 v[2:3], v[28:29], v[2:3]
	v_add_f32_e32 v8, v8, v7
	v_add_f32_e32 v8, v8, v3
	v_add_f32_e32 v8, v8, v2
	s_waitcnt lgkmcnt(0)
	v_lshlrev_b32_e32 v12, 16, v12
	v_add_f32_dpp v8, v8, v8 quad_perm:[1,0,3,2] row_mask:0xf bank_mask:0xf bound_ctrl:1
	s_nop 1
	v_add_f32_dpp v8, v8, v8 quad_perm:[2,3,0,1] row_mask:0xf bank_mask:0xf bound_ctrl:1
	s_nop 1
	v_add_f32_dpp v8, v8, v8 row_half_mirror row_mask:0xf bank_mask:0xf bound_ctrl:1
	s_nop 1
	v_add_f32_dpp v8, v8, v8 row_mirror row_mask:0xf bank_mask:0xf bound_ctrl:1
	v_mul_f32_e32 v8, 0x3c800000, v8
	v_pk_add_f32 v[6:7], v[6:7], v[8:9] op_sel_hi:[1,0] neg_lo:[0,1] neg_hi:[0,1]
	v_pk_add_f32 v[2:3], v[2:3], v[8:9] op_sel_hi:[1,0] neg_lo:[0,1] neg_hi:[0,1]
	v_pk_mul_f32 v[18:19], v[6:7], v[6:7]
	v_pk_mul_f32 v[20:21], v[2:3], v[2:3]
	v_add_f32_e32 v8, v18, v19
	v_add_f32_e32 v8, v21, v8
	v_add_f32_e32 v8, v20, v8
	s_nop 1
	v_add_f32_dpp v8, v8, v8 quad_perm:[1,0,3,2] row_mask:0xf bank_mask:0xf bound_ctrl:1
	s_nop 1
	v_add_f32_dpp v8, v8, v8 quad_perm:[2,3,0,1] row_mask:0xf bank_mask:0xf bound_ctrl:1
	s_nop 1
	v_add_f32_dpp v8, v8, v8 row_half_mirror row_mask:0xf bank_mask:0xf bound_ctrl:1
	s_nop 1
	v_add_f32_dpp v8, v8, v8 row_mirror row_mask:0xf bank_mask:0xf bound_ctrl:1
	v_fmamk_f32 v8, v8, 0x3c800000, v167
	v_cmp_gt_f32_e32 vcc, s20, v8
	v_mul_f32_e32 v11, 0x4b800000, v8
	s_nop 0
	v_cndmask_b32_e32 v8, v8, v11, vcc
	v_rsq_f32_e32 v8, v8
	s_nop 0
	v_mul_f32_e32 v11, 0x45800000, v8
	v_cndmask_b32_e32 v8, v8, v11, vcc
	ds_read_u16 v11, v94 offset:144
	v_mul_f32_e32 v6, v6, v8
	v_fmac_f32_e32 v38, v36, v6
	v_mul_f32_e32 v7, v7, v8
	v_fmac_f32_e32 v40, v37, v7
	s_waitcnt lgkmcnt(0)
	v_lshlrev_b32_e32 v11, 16, v11
	v_sub_f32_e32 v12, v12, v11
	v_fmac_f32_e32 v11, v30, v12
	v_mul_f32_e32 v3, v3, v8
	v_fmac_f32_e32 v35, v42, v3
	v_mul_f32_e32 v2, v2, v8
	v_fmac_f32_e32 v0, v14, v2
	s_waitcnt vmcnt(0)
	v_fmac_f32_e32 v38, v4, v11
	v_mul_f32_e32 v6, v9, v38
	v_cvt_pk_bf16_f32 v6, v6, v6
	ds_write_b16 v96, v6 offset:62464
	ds_read_u16 v6, v94 offset:176
	ds_read_u16 v9, v97
	s_waitcnt lgkmcnt(1)
	v_lshlrev_b32_e32 v6, 16, v6
	s_waitcnt lgkmcnt(0)
	v_lshlrev_b32_e32 v9, 16, v9
	v_sub_f32_e32 v9, v9, v6
	v_fmac_f32_e32 v6, v39, v9
	v_fmac_f32_e32 v40, v4, v6
	v_mul_f32_e32 v6, v13, v40
	v_cvt_pk_bf16_f32 v6, v6, v6
	ds_write_b16 v96, v6 offset:62496
	ds_read_u16 v6, v94 offset:208
	ds_read_u16 v7, v98
	s_waitcnt lgkmcnt(1)
	v_lshlrev_b32_e32 v6, 16, v6
	s_waitcnt lgkmcnt(0)
	v_lshlrev_b32_e32 v7, 16, v7
	v_sub_f32_e32 v7, v7, v6
	v_fmac_f32_e32 v6, v41, v7
	v_fmac_f32_e32 v35, v4, v6
	v_mul_f32_e32 v3, v17, v35
	v_cvt_pk_bf16_f32 v3, v3, v3
	ds_write_b16 v96, v3 offset:62528
	ds_read_u16 v3, v94 offset:240
	ds_read_u16 v6, v99
	s_waitcnt lgkmcnt(1)
	v_lshlrev_b32_e32 v3, 16, v3
	s_waitcnt lgkmcnt(0)
	v_lshlrev_b32_e32 v6, 16, v6
	v_sub_f32_e32 v6, v6, v3
	v_fmac_f32_e32 v3, v10, v6
	v_fmac_f32_e32 v0, v4, v3
	v_mul_f32_e32 v0, v5, v0
	v_cvt_pk_bf16_f32 v0, v0, v0
	ds_write_b16 v96, v0 offset:62560
	ds_read_b128 v[2:5], v105 offset:62464
	v_lshl_add_u64 v[6:7], s[16:17], 0, v[56:57]
	v_lshlrev_b64 v[6:7], 11, v[6:7]
	v_lshl_add_u64 v[6:7], s[58:59], 0, v[6:7]
	v_lshl_add_u64 v[6:7], v[6:7], 0, s[60:61]
	v_lshl_add_u64 v[6:7], v[6:7], 0, v[68:69]
	s_waitcnt lgkmcnt(0)
	global_store_dwordx4 v[6:7], v[2:5], off offset:1024
	ds_read_b128 v[2:5], v106 offset:62464
	v_lshl_add_u64 v[6:7], s[16:17], 0, v[64:65]
	v_lshlrev_b64 v[6:7], 11, v[6:7]
	v_lshl_add_u64 v[6:7], s[58:59], 0, v[6:7]
	v_lshl_add_u64 v[6:7], v[6:7], 0, s[60:61]
	v_lshl_add_u64 v[6:7], v[6:7], 0, v[68:69]
	s_waitcnt lgkmcnt(0)
	global_store_dwordx4 v[6:7], v[2:5], off offset:1024
	s_cbranch_scc1 .LBB0_660
